# v39: v32 + GLA-final item: the 16 forget-gate-sum loads are waited for at their first consumer (after the LDS write phase) instead of with everything at the item's first wait
# baseline (speedup 1.0000x reference)
; #define LAS __attribute__((address_space(3)))
; template <bool FINAL>
; DI void gla_unit(KA a, int l, int item, LAS unsigned char* lds) {
;     ...
;     f32x4 gnv[4];
;     if (FINAL) {
; #pragma unroll
;         for (int q = 0; q < 4; ++q) gnv[q] = *(const f32x4*)(a->in[20] + l * DV + vdvc + 4 * q);
;     }
;     ...
;     float bl[2][8];
;     {
;         float wg[2][16], bg[2];
; #pragma unroll
;         for (int hh = 0; hh < 2; ++hh) {
;             const float* wg2 = a->in[18] + (size_t)l * 16 * 256 + (2 * hp + hh) * 64 + dk;
; #pragma unroll
;             for (int e = 0; e < 16; ++e) wg[hh][e] = wg2[e * 256];
;             bg[hh] = a->in[19][l * 256 + (2 * hp + hh) * 64 + dk];
;         }
;         float run0 = 0.f, run1 = 0.f;
; #pragma unroll
;         for (int jj = 0; jj < 8; ++jj) {
;             const int t = 8 * tg + jj;
;             float ga = 0.f, gb = 0.f;
;             if (t < nvalid) {
;                 const u32x4* lp = (const u32x4*)(U + (size_t)(row0 + t) * UN + U_LR);
;                 float lr[16]; unpack8(lp[0], lr); unpack8(lp[1], lr + 8);
;                 float za = bg[0], zb = bg[1];
; #pragma unroll
;                 for (int e = 0; e < 16; ++e) { za += wg[0][e] * lr[e]; zb += wg[1][e] * lr[e]; }
;                 ga = (fminf(za, 0.f) - __logf(1.f + __expf(-fabsf(za)))) * (1.f / 16.f);
;                 gb = (fminf(zb, 0.f) - __logf(1.f + __expf(-fabsf(zb)))) * (1.f / 16.f);
;             }
;             run0 += ga; run1 += gb; bl[0][jj] = run0; bl[1][jj] = run1;
;         }
;         ((LAS float*)(lds + GL_GSUM))[tg * 64 + dk] = run0;
;         ((LAS float*)(lds + GL_HEAD + GL_GSUM))[tg * 64 + dk] = run1;
;     }
.LBB0_885:
	s_load_dwordx2 s[2:3], s[2:3], 0xa0
	s_lshl_b64 s[26:27], s[60:61], 2
	v_lshlrev_b32_e32 v124, 2, v167
	s_waitcnt lgkmcnt(0)
	s_add_u32 s2, s2, s26
	s_addc_u32 s3, s3, s27
	global_load_dwordx4 v[32:35], v124, s[2:3] offset:48
	global_load_dwordx4 v[52:55], v124, s[2:3] offset:32
	global_load_dwordx4 v[56:59], v124, s[2:3] offset:16
	global_load_dwordx4 v[60:63], v124, s[2:3]
	v_mov_b32_e32 v86, 0
	v_mov_b32_e32 v106, 0
	v_mov_b32_e32 v104, 0
	v_mov_b32_e32 v102, 0
	v_mov_b32_e32 v100, 0
	v_mov_b32_e32 v98, 0
	v_mov_b32_e32 v96, 0
	v_mov_b32_e32 v83, 0
	v_mov_b32_e32 v87, 0
	v_mov_b32_e32 v94, 0
	v_mov_b32_e32 v92, 0
	v_mov_b32_e32 v90, 0
	v_mov_b32_e32 v88, 0
	v_mov_b32_e32 v82, 0
	v_mov_b32_e32 v80, 0
	v_mov_b32_e32 v81, 0
	s_and_b64 vcc, exec, s[24:25]
	s_cbranch_vccnz .Lm3_bl_skip
	s_add_i32 s72, s53, s46
	s_lshl_b32 s72, s72, 11
	s_lshl_b32 s73, s54, 2
	s_add_i32 s72, s72, s73
	s_add_u32 s72, s30, s72
	s_addc_u32 s73, s31, 0
	s_add_u32 s72, s72, 0x5f00400
	s_addc_u32 s73, s73, 0
	s_add_u32 s74, s72, 0x1000
	s_addc_u32 s75, s73, 0
	s_add_u32 s76, s72, 0x2000
	s_addc_u32 s77, s73, 0
	s_add_u32 s78, s72, 0x3000
	s_addc_u32 s79, s73, 0
	v_lshlrev_b32_e32 v108, 2, v85
	global_load_dword v86, v108, s[72:73]
	global_load_dword v87, v108, s[72:73] offset:256
	global_load_dword v106, v108, s[72:73] offset:2048
	global_load_dword v94, v108, s[72:73] offset:2304
	global_load_dword v104, v108, s[74:75]
	global_load_dword v92, v108, s[74:75] offset:256
	global_load_dword v102, v108, s[74:75] offset:2048
	global_load_dword v90, v108, s[74:75] offset:2304
	global_load_dword v100, v108, s[76:77]
	global_load_dword v88, v108, s[76:77] offset:256
	global_load_dword v98, v108, s[76:77] offset:2048
	global_load_dword v82, v108, s[76:77] offset:2304
	global_load_dword v96, v108, s[78:79]
	global_load_dword v80, v108, s[78:79] offset:256
	global_load_dword v83, v108, s[78:79] offset:2048
	global_load_dword v81, v108, s[78:79] offset:2304
	s_waitcnt vmcnt(16)
	s_branch .Lm3_bl_join

; DI float bf2f(unsigned v) { return __uint_as_float(v << 16); }
; DI bf16_t f2bf(float f) { return (bf16_t)(cvt_pk(f, 0.f) & 0xffffu); }
; template <bool FINAL>
; DI void gla_unit(KA a, int l, int item, LAS unsigned char* lds) {
;     ...
;             for (int it = 0; it < 4; ++it) {
;                 const int idx = it * 512 + tid; sv[hh][it] = (f32x4){0.f, 0.f, 0.f, 0.f};
;                 if (S0[hh]) sv[hh][it] = *(const f32x4*)(S0[hh] + (idx >> 5) * 128 + (idx & 31) * 4);
;                 else if (Sb) { const u32x2 v = *(const u32x2*)(Sb + (idx >> 5) * 128 + (idx & 31) * 4); sv[hh][it] = (f32x4){bf2f(v.x & 0xffffu), __uint_as_float(v.x & 0xffff0000u), bf2f(v.y & 0xffffu), __uint_as_float(v.y & 0xffff0000u)}; }
;             }
;         }
;     ...
;             if (FINAL) { qs[t * 72 + dk] = f2bf(bf2f(qraw[hh][jj]) * 0.125f * __expf(bj)); ks[t * 72 + dk] = f2bf(kv * __expf(-bj)); }
.Lm3_bl_join:
.LBB0_901:
	v_mul_f32_e32 v140, 0x3e000000, v140
	v_mul_f32_e32 v136, 0x3e000000, v136
	v_mul_f32_e32 v138, 0x3e000000, v138
	v_mul_f32_e32 v132, 0x3e000000, v132
	v_mul_f32_e32 v135, 0x3e000000, v135
	v_mul_f32_e32 v128, 0x3e000000, v128
	v_mul_f32_e32 v131, 0x3e000000, v131
	v_mul_f32_e32 v125, 0x3e000000, v125
	v_mul_f32_e32 v154, 0x3e000000, v154
	v_mul_f32_e32 v141, 0x3e000000, v141
	v_mul_f32_e32 v157, 0x3e000000, v157
	v_mul_f32_e32 v143, 0x3e000000, v143
	v_mul_f32_e32 v161, 0x3e000000, v161
	v_mul_f32_e32 v159, 0x3e000000, v159
	v_mul_f32_e32 v165, 0x3e000000, v165
	v_mul_f32_e32 v163, 0x3e000000, v163
	s_andn2_b64 vcc, exec, s[66:67]
	s_cbranch_vccnz .Lm3_nu0
	v_lshlrev_b32_e32 v8, 16, v10
	v_and_b32_e32 v9, 0xffff0000, v10
	v_lshlrev_b32_e32 v10, 16, v11
	v_and_b32_e32 v11, 0xffff0000, v11
	v_lshlrev_b32_e32 v12, 16, v14
	v_and_b32_e32 v13, 0xffff0000, v14
	v_lshlrev_b32_e32 v14, 16, v15
	v_and_b32_e32 v15, 0xffff0000, v15
	v_lshlrev_b32_e32 v16, 16, v18
	v_and_b32_e32 v17, 0xffff0000, v18
	v_lshlrev_b32_e32 v18, 16, v19
	v_and_b32_e32 v19, 0xffff0000, v19
	v_lshlrev_b32_e32 v20, 16, v22
	v_and_b32_e32 v21, 0xffff0000, v22
	v_lshlrev_b32_e32 v22, 16, v23
	v_and_b32_e32 v23, 0xffff0000, v23

; #define LAS __attribute__((address_space(3)))
; DI bf16_t f2bf(float f) { return (bf16_t)(cvt_pk(f, 0.f) & 0xffffu); }
; #define LBAR() do { asm volatile("s_waitcnt lgkmcnt(0)" ::: "memory"); __builtin_amdgcn_s_barrier(); asm volatile("" ::: "memory"); } while (0)
; template <bool FINAL>
; DI void gla_unit(KA a, int l, int item, LAS unsigned char* lds) {
;     ...
;         LAS bf16_t* vT = (LAS bf16_t*)(lds + hh * GL_HEAD + GL_VT); LAS bf16_t* sT = (LAS bf16_t*)(lds + hh * GL_HEAD + GL_ST);
;         {
;             const unsigned vv[8] = {v0[hh].x, v0[hh].y, v0[hh].z, v0[hh].w, v1[hh].x, v1[hh].y, v1[hh].z, v1[hh].w};
;             const int col = ((((vj >> 3) ^ ((vdvc >> 4) & 7)) << 3) | (vj & 7));
; #pragma unroll
;             for (int e = 0; e < 8; ++e) { vT[(vdvc + 2 * e) * 72 + col] = (bf16_t)(vv[e] & 0xffffu); vT[(vdvc + 2 * e + 1) * 72 + col] = (bf16_t)(vv[e] >> 16); }
;         }
;         if (FINAL) {
; #pragma unroll
;             for (int it = 0; it < 4; ++it) {
;                 const int idx = it * 512 + tid, dkk = idx >> 5, dv4 = (idx & 31) * 4;
;                 const int col = ((((dkk >> 3) ^ ((dv4 >> 4) & 7)) << 3) | (dkk & 7));
;                 sT[(dv4 + 0) * 72 + col] = f2bf(sv[hh][it].x); sT[(dv4 + 1) * 72 + col] = f2bf(sv[hh][it].y); sT[(dv4 + 2) * 72 + col] = f2bf(sv[hh][it].z); sT[(dv4 + 3) * 72 + col] = f2bf(sv[hh][it].w);
;             }
;         }
;     }
;     LBAR();
.Lm3_nu1:
	v_ashrrev_i32_e32 v89, 6, v123
	v_lshrrev_b32_e32 v97, 2, v123
	v_bitop3_b32 v89, v89, v123, 7 bitop3:0x78
	v_and_b32_e32 v97, 14, v97
	v_mul_u32_u24_e32 v95, 0x90, v167
	v_lshl_or_b32 v89, v89, 4, v97
	v_add3_u32 v95, 0, v95, v89
	v_lshrrev_b32_e32 v91, 4, v169
	v_ashrrev_i32_e32 v93, 8, v123
	ds_write_b16 v95, v4 offset:22528
	ds_write_b16_d16_hi v95, v4 offset:22672
	ds_write_b16 v95, v5 offset:22816
	ds_write_b16_d16_hi v95, v5 offset:22960
	ds_write_b16 v95, v6 offset:23104
	ds_write_b16_d16_hi v95, v6 offset:23248
	ds_write_b16 v95, v7 offset:23392
	ds_write_b16_d16_hi v95, v7 offset:23536
	ds_write_b16 v95, v0 offset:23680
	ds_write_b16_d16_hi v95, v0 offset:23824
	ds_write_b16 v95, v1 offset:23968
	ds_write_b16_d16_hi v95, v1 offset:24112
	ds_write_b16 v95, v2 offset:24256
	ds_write_b16_d16_hi v95, v2 offset:24400
	ds_write_b16 v95, v3 offset:24544
	ds_write_b16_d16_hi v95, v3 offset:24688
	v_lshrrev_b32_e32 v95, 4, v123
	v_bitop3_b32 v93, v91, v93, 7 bitop3:0x6c
	s_movk_i32 s0, 0x90
	v_and_b32_e32 v95, 14, v95
	v_mad_u32_u24 v3, v168, s0, 0
	v_lshl_or_b32 v93, v93, 4, v95
	v_cvt_pk_bf16_f32 v8, v8, v145
	v_add_u32_e32 v97, v3, v93
	ds_write_b16 v97, v8 offset:40960
	v_cvt_pk_bf16_f32 v8, v9, v145
	ds_write_b16 v97, v8 offset:41104
	v_cvt_pk_bf16_f32 v8, v10, v145
	ds_write_b16 v97, v8 offset:41248
	v_cvt_pk_bf16_f32 v8, v11, v145
	ds_write_b16 v97, v8 offset:41392
	v_ashrrev_i32_e32 v8, 8, v170
	v_bitop3_b32 v8, v91, v8, 7 bitop3:0x6c
	v_lshl_or_b32 v8, v8, 4, v95
	v_cvt_pk_bf16_f32 v9, v12, v145
	v_add_u32_e32 v10, v3, v8
	ds_write_b16 v10, v9 offset:40960
	v_cvt_pk_bf16_f32 v9, v13, v145
	ds_write_b16 v10, v9 offset:41104
	v_cvt_pk_bf16_f32 v9, v14, v145
	ds_write_b16 v10, v9 offset:41248
	v_cvt_pk_bf16_f32 v9, v15, v145
	ds_write_b16 v10, v9 offset:41392
	v_ashrrev_i32_e32 v9, 8, v171
	v_bitop3_b32 v9, v91, v9, 7 bitop3:0x6c
	v_lshl_or_b32 v9, v9, 4, v95
	v_cvt_pk_bf16_f32 v10, v16, v145
	v_add_u32_e32 v11, v3, v9
	ds_write_b16 v11, v10 offset:40960
	v_cvt_pk_bf16_f32 v10, v17, v145
	ds_write_b16 v11, v10 offset:41104
	v_cvt_pk_bf16_f32 v10, v18, v145
	ds_write_b16 v11, v10 offset:41248
	v_cvt_pk_bf16_f32 v10, v19, v145
	ds_write_b16 v11, v10 offset:41392
	v_ashrrev_i32_e32 v10, 8, v172
	v_bitop3_b32 v10, v91, v10, 7 bitop3:0x6c
	v_lshl_or_b32 v10, v10, 4, v95
	v_cvt_pk_bf16_f32 v11, v20, v145
	v_add_u32_e32 v3, v3, v10
	ds_write_b16 v3, v11 offset:40960
	v_cvt_pk_bf16_f32 v11, v21, v145
	ds_write_b16 v3, v11 offset:41104
	v_cvt_pk_bf16_f32 v11, v22, v145
	v_readlane_b32 s2, v254, 47
	ds_write_b16 v3, v11 offset:41248
	v_cvt_pk_bf16_f32 v11, v23, v145
	ds_write_b16 v3, v11 offset:41392
	v_add_u32_e32 v3, s2, v89
	v_mad_u32_u24 v4, v167, s0, v223
	v_mad_u32_u24 v11, v167, s0, v3
	v_mad_u32_u24 v5, v167, s0, v224
	ds_write_b16 v11, v28
	ds_write_b16_d16_hi v11, v28 offset:144
	v_add_u32_e32 v11, v3, v4
	v_add3_u32 v4, s2, v4, v89
	ds_write_b16_d16_hi v4, v29 offset:144
	v_add_u32_e32 v4, v3, v5
	v_mad_u32_u24 v6, v167, s0, v225
	ds_write_b16 v4, v30
	v_add3_u32 v4, s2, v5, v89
	ds_write_b16_d16_hi v4, v30 offset:144
	v_add_u32_e32 v4, v3, v6
	v_mad_u32_u24 v7, v167, s0, v226
	ds_write_b16 v4, v31
	v_add3_u32 v4, s2, v6, v89
	ds_write_b16_d16_hi v4, v31 offset:144
	v_add_u32_e32 v4, v3, v7
	v_mad_u32_u24 v0, v167, s0, v227
	ds_write_b16 v4, v24
	v_add3_u32 v4, s2, v7, v89
	v_mad_u32_u24 v1, v167, s0, v228
	ds_write_b16_d16_hi v4, v24 offset:144
	v_add_u32_e32 v4, v3, v0
	v_add3_u32 v0, s2, v0, v89
	ds_write_b16_d16_hi v0, v25 offset:144
	v_add_u32_e32 v0, v3, v1
	v_mad_u32_u24 v2, v167, s0, v229
	ds_write_b16 v0, v26
	v_add3_u32 v0, s2, v1, v89
	ds_write_b16_d16_hi v0, v26 offset:144
	v_add_u32_e32 v0, v3, v2
	ds_write_b16 v0, v27
	v_add3_u32 v0, s2, v2, v89
	v_readlane_b32 s2, v254, 48
	ds_write_b16_d16_hi v0, v27 offset:144
	v_cvt_pk_bf16_f32 v1, v64, v145
	ds_write_b16 v11, v29
	v_mov_b32_e32 v0, s2
	v_mad_u32_u24 v0, v168, s0, v0
	v_add_u32_e32 v2, v0, v93
	ds_write_b16 v4, v25
	ds_write_b16 v2, v1
	v_cvt_pk_bf16_f32 v1, v65, v145
	ds_write_b16 v2, v1 offset:144
	v_cvt_pk_bf16_f32 v1, v66, v145
	ds_write_b16 v2, v1 offset:288
	v_cvt_pk_bf16_f32 v1, v67, v145
	ds_write_b16 v2, v1 offset:432
	v_cvt_pk_bf16_f32 v1, v68, v145
	v_add_u32_e32 v2, v0, v8
	ds_write_b16 v2, v1
	v_cvt_pk_bf16_f32 v1, v69, v145
	ds_write_b16 v2, v1 offset:144
	v_cvt_pk_bf16_f32 v1, v70, v145
	ds_write_b16 v2, v1 offset:288
	v_cvt_pk_bf16_f32 v1, v71, v145
	ds_write_b16 v2, v1 offset:432
	v_cvt_pk_bf16_f32 v1, v72, v145
	v_add_u32_e32 v2, v0, v9
	ds_write_b16 v2, v1
	v_cvt_pk_bf16_f32 v1, v73, v145
	ds_write_b16 v2, v1 offset:144
	v_cvt_pk_bf16_f32 v1, v74, v145
	ds_write_b16 v2, v1 offset:288
	v_cvt_pk_bf16_f32 v1, v75, v145
	ds_write_b16 v2, v1 offset:432
	v_cvt_pk_bf16_f32 v1, v76, v145
	v_add_u32_e32 v0, v0, v10
	ds_write_b16 v0, v1
	v_cvt_pk_bf16_f32 v1, v77, v145
	ds_write_b16 v0, v1 offset:144
	v_cvt_pk_bf16_f32 v1, v78, v145
	ds_write_b16 v0, v1 offset:288
	v_cvt_pk_bf16_f32 v1, v79, v145
	ds_write_b16 v0, v1 offset:432
	s_waitcnt vmcnt(0)
	s_waitcnt lgkmcnt(0)
	s_barrier
	v_mov_b32_e32 v2, 0
